# K-loop: dropped the redundant second lgkmcnt wait after each phase barrier
# speedup vs baseline: 1.0020x; 1.0020x over previous
.LBB0_691:
	s_add_u32 s57, s10, 0x100
	s_addc_u32 vcc_lo, s11, 0
	s_add_u32 s38, s52, 0x80
	s_addc_u32 s39, s53, 0
	s_mov_b32 s10, 0
	s_add_i32 s52, s10, 2
	s_add_u32 s33, s38, 0x80
	s_addc_u32 s11, s39, 0
	s_add_i32 s34, 0, 0x10000
	s_cmp_eq_u32 s95, s10
	s_cselect_b32 s11, s9, s11
	s_cselect_b32 s10, s8, s33
	s_cselect_b32 s73, s1, vcc_lo
	s_cselect_b32 s72, s0, s57
	s_add_i32 s33, 0, 0x14000
	v_add_u32_e32 v230, s34, v223
	v_add_u32_e32 v231, s33, v223
	ds_read_b128 v[130:133], v230
	ds_read_b128 v[134:137], v230 offset:1024
	ds_read_b128 v[138:141], v230 offset:2048
	ds_read_b128 v[156:159], v230 offset:3072
	ds_read_b128 v[160:163], v231
	ds_read_b128 v[164:167], v231 offset:1024
	ds_read_b128 v[168:171], v231 offset:2048
	ds_read_b128 v[172:175], v231 offset:3072
	s_add_i32 m0, s20, 0xc000
	ds_read_b128 v[176:179], v225
	ds_read_b128 v[180:183], v225 offset:1024
	ds_read_b128 v[184:187], v225 offset:2048
	ds_read_b128 v[188:191], v225 offset:3072
	ds_read_b128 v[192:195], v225 offset:4096
	ds_read_b128 v[196:199], v225 offset:5120
	ds_read_b128 v[200:203], v225 offset:6144
	ds_read_b128 v[226:229], v225 offset:7168
	global_load_lds_dwordx4 v154, s[38:39]
	s_add_i32 m0, s20, 0xe000
	s_nop 0
	global_load_lds_dwordx4 v152, s[38:39]
	s_waitcnt vmcnt(8)
	s_waitcnt lgkmcnt(0)
	s_barrier
	s_setprio 1
	v_mfma_f32_16x16x32_bf16 v[126:129], v[130:133], v[176:179], 0
	v_mfma_f32_16x16x32_bf16 v[122:125], v[138:141], v[176:179], 0
	v_mfma_f32_16x16x32_bf16 v[110:113], v[130:133], v[184:187], 0
	v_mfma_f32_16x16x32_bf16 v[106:109], v[138:141], v[184:187], 0
	v_mfma_f32_16x16x32_bf16 v[94:97], v[130:133], v[192:195], 0
	v_mfma_f32_16x16x32_bf16 v[90:93], v[138:141], v[192:195], 0
	v_mfma_f32_16x16x32_bf16 v[78:81], v[130:133], v[200:203], 0
	v_mfma_f32_16x16x32_bf16 v[74:77], v[138:141], v[200:203], 0
	v_mfma_f32_16x16x32_bf16 v[126:129], v[134:137], v[180:183], v[126:129]
	v_mfma_f32_16x16x32_bf16 v[122:125], v[156:159], v[180:183], v[122:125]
	v_mfma_f32_16x16x32_bf16 v[110:113], v[134:137], v[188:191], v[110:113]
	v_mfma_f32_16x16x32_bf16 v[106:109], v[156:159], v[188:191], v[106:109]
	v_mfma_f32_16x16x32_bf16 v[94:97], v[134:137], v[196:199], v[94:97]
	v_mfma_f32_16x16x32_bf16 v[90:93], v[156:159], v[196:199], v[90:93]
	v_mfma_f32_16x16x32_bf16 v[78:81], v[134:137], v[226:229], v[78:81]
	v_mfma_f32_16x16x32_bf16 v[74:77], v[156:159], v[226:229], v[74:77]
	s_setprio 0
	s_setprio 1
	v_mfma_f32_16x16x32_bf16 v[118:121], v[160:163], v[176:179], 0
	v_mfma_f32_16x16x32_bf16 v[114:117], v[168:171], v[176:179], 0
	v_mfma_f32_16x16x32_bf16 v[102:105], v[160:163], v[184:187], 0
	v_mfma_f32_16x16x32_bf16 v[98:101], v[168:171], v[184:187], 0
	v_mfma_f32_16x16x32_bf16 v[86:89], v[160:163], v[192:195], 0
	v_mfma_f32_16x16x32_bf16 v[82:85], v[168:171], v[192:195], 0
	v_mfma_f32_16x16x32_bf16 v[70:73], v[160:163], v[200:203], 0
	v_mfma_f32_16x16x32_bf16 v[66:69], v[168:171], v[200:203], 0
	v_mfma_f32_16x16x32_bf16 v[118:121], v[164:167], v[180:183], v[118:121]
	v_mfma_f32_16x16x32_bf16 v[114:117], v[172:175], v[180:183], v[114:117]
	v_mfma_f32_16x16x32_bf16 v[102:105], v[164:167], v[188:191], v[102:105]
	v_mfma_f32_16x16x32_bf16 v[98:101], v[172:175], v[188:191], v[98:101]
	v_mfma_f32_16x16x32_bf16 v[86:89], v[164:167], v[196:199], v[86:89]
	v_mfma_f32_16x16x32_bf16 v[82:85], v[172:175], v[196:199], v[82:85]
	v_mfma_f32_16x16x32_bf16 v[70:73], v[164:167], v[226:229], v[70:73]
	v_mfma_f32_16x16x32_bf16 v[66:69], v[172:175], v[226:229], v[66:69]
	s_setprio 0
	s_barrier
	s_add_i32 s34, s34, s29
	s_mov_b32 m0, s34
	ds_read_b128 v[176:179], v225 offset:16384
	ds_read_b128 v[180:183], v225 offset:17408
	ds_read_b128 v[184:187], v225 offset:18432
	ds_read_b128 v[188:191], v225 offset:19456
	ds_read_b128 v[192:195], v225 offset:20480
	ds_read_b128 v[196:199], v225 offset:21504
	ds_read_b128 v[200:203], v225 offset:22528
	ds_read_b128 v[226:229], v225 offset:23552
	global_load_lds_dwordx4 v0, s[72:73]
	s_add_i32 m0, s34, 0x2000
	s_mov_b64 s[98:99], s[72:73]
	s_add_i32 s33, s33, s29
	global_load_lds_dwordx4 v150, s[72:73]
	s_add_u32 s72, s72, s46
	s_addc_u32 s73, s73, 0
	s_mov_b32 m0, s33
	s_mov_b64 s[100:101], s[10:11]
	global_load_lds_dwordx4 v0, s[72:73]
	s_add_i32 m0, s33, 0x2000
	s_nop 0
	global_load_lds_dwordx4 v150, s[72:73]
	s_mov_b32 m0, s20
	s_nop 0
	global_load_lds_dwordx4 v146, s[10:11]
	s_mov_b32 m0, s35
	s_nop 0
	global_load_lds_dwordx4 v148, s[10:11]
	s_waitcnt vmcnt(8)
	s_waitcnt lgkmcnt(0)
	s_barrier
	s_setprio 1
	v_mfma_f32_16x16x32_bf16 v[62:65], v[130:133], v[176:179], 0
	v_mfma_f32_16x16x32_bf16 v[58:61], v[138:141], v[176:179], 0
	v_mfma_f32_16x16x32_bf16 v[46:49], v[130:133], v[184:187], 0
	v_mfma_f32_16x16x32_bf16 v[42:45], v[138:141], v[184:187], 0
	v_mfma_f32_16x16x32_bf16 v[30:33], v[130:133], v[192:195], 0
	v_mfma_f32_16x16x32_bf16 v[26:29], v[138:141], v[192:195], 0
	v_mfma_f32_16x16x32_bf16 v[14:17], v[130:133], v[200:203], 0
	v_mfma_f32_16x16x32_bf16 v[10:13], v[138:141], v[200:203], 0
	v_mfma_f32_16x16x32_bf16 v[62:65], v[134:137], v[180:183], v[62:65]
	v_mfma_f32_16x16x32_bf16 v[58:61], v[156:159], v[180:183], v[58:61]
	v_mfma_f32_16x16x32_bf16 v[46:49], v[134:137], v[188:191], v[46:49]
	v_mfma_f32_16x16x32_bf16 v[42:45], v[156:159], v[188:191], v[42:45]
	v_mfma_f32_16x16x32_bf16 v[30:33], v[134:137], v[196:199], v[30:33]
	v_mfma_f32_16x16x32_bf16 v[26:29], v[156:159], v[196:199], v[26:29]
	v_mfma_f32_16x16x32_bf16 v[14:17], v[134:137], v[226:229], v[14:17]
	v_mfma_f32_16x16x32_bf16 v[10:13], v[156:159], v[226:229], v[10:13]
	s_setprio 0
	s_setprio 1
	v_mfma_f32_16x16x32_bf16 v[54:57], v[160:163], v[176:179], 0
	v_mfma_f32_16x16x32_bf16 v[50:53], v[168:171], v[176:179], 0
	v_mfma_f32_16x16x32_bf16 v[38:41], v[160:163], v[184:187], 0
	v_mfma_f32_16x16x32_bf16 v[34:37], v[168:171], v[184:187], 0
	v_mfma_f32_16x16x32_bf16 v[22:25], v[160:163], v[192:195], 0
	v_mfma_f32_16x16x32_bf16 v[18:21], v[168:171], v[192:195], 0
	v_mfma_f32_16x16x32_bf16 v[6:9], v[160:163], v[200:203], 0
	v_mfma_f32_16x16x32_bf16 v[2:5], v[168:171], v[200:203], 0
	v_mfma_f32_16x16x32_bf16 v[54:57], v[164:167], v[180:183], v[54:57]
	v_mfma_f32_16x16x32_bf16 v[50:53], v[172:175], v[180:183], v[50:53]
	v_mfma_f32_16x16x32_bf16 v[38:41], v[164:167], v[188:191], v[38:41]
	v_mfma_f32_16x16x32_bf16 v[34:37], v[172:175], v[188:191], v[34:37]
	v_mfma_f32_16x16x32_bf16 v[22:25], v[164:167], v[196:199], v[22:25]
	v_mfma_f32_16x16x32_bf16 v[18:21], v[172:175], v[196:199], v[18:21]
	v_mfma_f32_16x16x32_bf16 v[6:9], v[164:167], v[226:229], v[6:9]
	v_mfma_f32_16x16x32_bf16 v[2:5], v[172:175], v[226:229], v[2:5]
	s_setprio 0
	s_barrier
	s_add_i32 s33, 0, 0x18000
	s_add_i32 s34, 0, 0x1c000
	v_add_u32_e32 v232, s33, v223
	v_add_u32_e32 v233, s34, v223
	ds_read_b128 v[130:133], v232
	ds_read_b128 v[134:137], v232 offset:1024
	ds_read_b128 v[138:141], v232 offset:2048
	ds_read_b128 v[156:159], v232 offset:3072
	ds_read_b128 v[160:163], v233
	ds_read_b128 v[164:167], v233 offset:1024
	ds_read_b128 v[168:171], v233 offset:2048
	ds_read_b128 v[172:175], v233 offset:3072
	s_add_u32 s10, s10, s46
	s_addc_u32 s11, s11, 0
	s_mov_b32 m0, s93
	ds_read_b128 v[176:179], v225 offset:32768
	ds_read_b128 v[180:183], v225 offset:33792
	ds_read_b128 v[184:187], v225 offset:34816
	ds_read_b128 v[188:191], v225 offset:35840
	ds_read_b128 v[192:195], v225 offset:36864
	ds_read_b128 v[196:199], v225 offset:37888
	ds_read_b128 v[200:203], v225 offset:38912
	ds_read_b128 v[226:229], v225 offset:39936
	global_load_lds_dwordx4 v146, s[10:11]
	s_mov_b32 m0, s83
	s_nop 0
	global_load_lds_dwordx4 v148, s[10:11]
	s_waitcnt vmcnt(8)
	s_waitcnt lgkmcnt(0)
	s_barrier
	s_setprio 1
	v_mfma_f32_16x16x32_bf16 v[126:129], v[130:133], v[176:179], v[126:129]
	v_mfma_f32_16x16x32_bf16 v[122:125], v[138:141], v[176:179], v[122:125]
	v_mfma_f32_16x16x32_bf16 v[110:113], v[130:133], v[184:187], v[110:113]
	v_mfma_f32_16x16x32_bf16 v[106:109], v[138:141], v[184:187], v[106:109]
	v_mfma_f32_16x16x32_bf16 v[94:97], v[130:133], v[192:195], v[94:97]
	v_mfma_f32_16x16x32_bf16 v[90:93], v[138:141], v[192:195], v[90:93]
	v_mfma_f32_16x16x32_bf16 v[78:81], v[130:133], v[200:203], v[78:81]
	v_mfma_f32_16x16x32_bf16 v[74:77], v[138:141], v[200:203], v[74:77]
	v_mfma_f32_16x16x32_bf16 v[126:129], v[134:137], v[180:183], v[126:129]
	v_mfma_f32_16x16x32_bf16 v[122:125], v[156:159], v[180:183], v[122:125]
	v_mfma_f32_16x16x32_bf16 v[110:113], v[134:137], v[188:191], v[110:113]
	v_mfma_f32_16x16x32_bf16 v[106:109], v[156:159], v[188:191], v[106:109]
	v_mfma_f32_16x16x32_bf16 v[94:97], v[134:137], v[196:199], v[94:97]
	v_mfma_f32_16x16x32_bf16 v[90:93], v[156:159], v[196:199], v[90:93]
	v_mfma_f32_16x16x32_bf16 v[78:81], v[134:137], v[226:229], v[78:81]
	v_mfma_f32_16x16x32_bf16 v[74:77], v[156:159], v[226:229], v[74:77]
	s_setprio 0
	s_setprio 1
	v_mfma_f32_16x16x32_bf16 v[118:121], v[160:163], v[176:179], v[118:121]
	v_mfma_f32_16x16x32_bf16 v[114:117], v[168:171], v[176:179], v[114:117]
	v_mfma_f32_16x16x32_bf16 v[102:105], v[160:163], v[184:187], v[102:105]
	v_mfma_f32_16x16x32_bf16 v[98:101], v[168:171], v[184:187], v[98:101]
	v_mfma_f32_16x16x32_bf16 v[86:89], v[160:163], v[192:195], v[86:89]
	v_mfma_f32_16x16x32_bf16 v[82:85], v[168:171], v[192:195], v[82:85]
	v_mfma_f32_16x16x32_bf16 v[70:73], v[160:163], v[200:203], v[70:73]
	v_mfma_f32_16x16x32_bf16 v[66:69], v[168:171], v[200:203], v[66:69]
	v_mfma_f32_16x16x32_bf16 v[118:121], v[164:167], v[180:183], v[118:121]
	v_mfma_f32_16x16x32_bf16 v[114:117], v[172:175], v[180:183], v[114:117]
	v_mfma_f32_16x16x32_bf16 v[102:105], v[164:167], v[188:191], v[102:105]
	v_mfma_f32_16x16x32_bf16 v[98:101], v[172:175], v[188:191], v[98:101]
	v_mfma_f32_16x16x32_bf16 v[86:89], v[164:167], v[196:199], v[86:89]
	v_mfma_f32_16x16x32_bf16 v[82:85], v[172:175], v[196:199], v[82:85]
	v_mfma_f32_16x16x32_bf16 v[70:73], v[164:167], v[226:229], v[70:73]
	v_mfma_f32_16x16x32_bf16 v[66:69], v[172:175], v[226:229], v[66:69]
	s_setprio 0
	s_barrier
	s_add_i32 s10, s33, s29
	s_mov_b32 m0, s10
	s_add_u32 s98, s98, 0x80
	s_addc_u32 s99, s99, 0
	ds_read_b128 v[176:179], v225 offset:49152
	ds_read_b128 v[180:183], v225 offset:50176
	ds_read_b128 v[184:187], v225 offset:51200
	ds_read_b128 v[188:191], v225 offset:52224
	ds_read_b128 v[192:195], v225 offset:53248
	ds_read_b128 v[196:199], v225 offset:54272
	ds_read_b128 v[200:203], v225 offset:55296
	ds_read_b128 v[226:229], v225 offset:56320
	global_load_lds_dwordx4 v0, s[98:99]
	s_add_i32 m0, s10, 0x2000
	s_add_i32 s10, s34, s29
	global_load_lds_dwordx4 v150, s[98:99]
	s_mov_b32 m0, s10
	s_add_u32 s72, s72, 0x80
	s_addc_u32 s73, s73, 0
	global_load_lds_dwordx4 v0, s[72:73]
	s_add_i32 m0, s10, 0x2000
	s_add_u32 s100, s100, 0x80
	s_addc_u32 s101, s101, 0
	global_load_lds_dwordx4 v150, s[72:73]
	s_mov_b32 m0, s96
	s_nop 0
	global_load_lds_dwordx4 v146, s[100:101]
	s_mov_b32 m0, s97
	s_nop 0
	global_load_lds_dwordx4 v148, s[100:101]
	s_waitcnt vmcnt(8)
	s_waitcnt lgkmcnt(0)
	s_barrier
	s_setprio 1
	v_mfma_f32_16x16x32_bf16 v[62:65], v[130:133], v[176:179], v[62:65]
	v_mfma_f32_16x16x32_bf16 v[58:61], v[138:141], v[176:179], v[58:61]
	v_mfma_f32_16x16x32_bf16 v[46:49], v[130:133], v[184:187], v[46:49]
	v_mfma_f32_16x16x32_bf16 v[42:45], v[138:141], v[184:187], v[42:45]
	v_mfma_f32_16x16x32_bf16 v[30:33], v[130:133], v[192:195], v[30:33]
	v_mfma_f32_16x16x32_bf16 v[26:29], v[138:141], v[192:195], v[26:29]
	v_mfma_f32_16x16x32_bf16 v[14:17], v[130:133], v[200:203], v[14:17]
	v_mfma_f32_16x16x32_bf16 v[10:13], v[138:141], v[200:203], v[10:13]
	v_mfma_f32_16x16x32_bf16 v[62:65], v[134:137], v[180:183], v[62:65]
	v_mfma_f32_16x16x32_bf16 v[58:61], v[156:159], v[180:183], v[58:61]
	v_mfma_f32_16x16x32_bf16 v[46:49], v[134:137], v[188:191], v[46:49]
	v_mfma_f32_16x16x32_bf16 v[42:45], v[156:159], v[188:191], v[42:45]
	v_mfma_f32_16x16x32_bf16 v[30:33], v[134:137], v[196:199], v[30:33]
	v_mfma_f32_16x16x32_bf16 v[26:29], v[156:159], v[196:199], v[26:29]
	v_mfma_f32_16x16x32_bf16 v[14:17], v[134:137], v[226:229], v[14:17]
	v_mfma_f32_16x16x32_bf16 v[10:13], v[156:159], v[226:229], v[10:13]
	s_setprio 0
	s_setprio 1
	v_mfma_f32_16x16x32_bf16 v[54:57], v[160:163], v[176:179], v[54:57]
	v_mfma_f32_16x16x32_bf16 v[50:53], v[168:171], v[176:179], v[50:53]
	v_mfma_f32_16x16x32_bf16 v[38:41], v[160:163], v[184:187], v[38:41]
	v_mfma_f32_16x16x32_bf16 v[34:37], v[168:171], v[184:187], v[34:37]
	v_mfma_f32_16x16x32_bf16 v[22:25], v[160:163], v[192:195], v[22:25]
	v_mfma_f32_16x16x32_bf16 v[18:21], v[168:171], v[192:195], v[18:21]
	v_mfma_f32_16x16x32_bf16 v[6:9], v[160:163], v[200:203], v[6:9]
	v_mfma_f32_16x16x32_bf16 v[2:5], v[168:171], v[200:203], v[2:5]
	v_mfma_f32_16x16x32_bf16 v[54:57], v[164:167], v[180:183], v[54:57]
	v_mfma_f32_16x16x32_bf16 v[50:53], v[172:175], v[180:183], v[50:53]
	v_mfma_f32_16x16x32_bf16 v[38:41], v[164:167], v[188:191], v[38:41]
	v_mfma_f32_16x16x32_bf16 v[34:37], v[172:175], v[188:191], v[34:37]
	v_mfma_f32_16x16x32_bf16 v[22:25], v[164:167], v[196:199], v[22:25]
	v_mfma_f32_16x16x32_bf16 v[18:21], v[172:175], v[196:199], v[18:21]
	v_mfma_f32_16x16x32_bf16 v[6:9], v[164:167], v[226:229], v[6:9]
	v_mfma_f32_16x16x32_bf16 v[2:5], v[172:175], v[226:229], v[2:5]
	s_setprio 0
	s_barrier
	s_add_u32 s57, s57, 0x100
	s_addc_u32 vcc_lo, vcc_lo, 0
	s_add_u32 s38, s38, 0x100
	s_addc_u32 s39, s39, 0
	s_cmp_ge_u32 s52, s22
	s_mov_b32 s10, s52
	s_cbranch_scc0 .LBB0_692
	s_branch .Lkloop_exit
.LBB0_692:
	s_add_i32 s52, s10, 2
	s_add_u32 s33, s38, 0x80
	s_addc_u32 s11, s39, 0
	s_add_i32 s34, 0, 0x10000
	s_cmp_eq_u32 s95, s10
	s_cselect_b32 s11, s9, s11
	s_cselect_b32 s10, s8, s33
	s_cselect_b32 s73, s1, vcc_lo
	s_cselect_b32 s72, s0, s57
	s_add_i32 s33, 0, 0x14000
	ds_read_b128 v[130:133], v230
	ds_read_b128 v[134:137], v230 offset:1024
	ds_read_b128 v[138:141], v230 offset:2048
	ds_read_b128 v[156:159], v230 offset:3072
	ds_read_b128 v[160:163], v231
	ds_read_b128 v[164:167], v231 offset:1024
	ds_read_b128 v[168:171], v231 offset:2048
	ds_read_b128 v[172:175], v231 offset:3072
	s_add_i32 m0, s20, 0xc000
	ds_read_b128 v[176:179], v225
	ds_read_b128 v[180:183], v225 offset:1024
	ds_read_b128 v[184:187], v225 offset:2048
	ds_read_b128 v[188:191], v225 offset:3072
	ds_read_b128 v[192:195], v225 offset:4096
	ds_read_b128 v[196:199], v225 offset:5120
	ds_read_b128 v[200:203], v225 offset:6144
	ds_read_b128 v[226:229], v225 offset:7168
	global_load_lds_dwordx4 v154, s[38:39]
	s_add_i32 m0, s20, 0xe000
	s_nop 0
	global_load_lds_dwordx4 v152, s[38:39]
	s_waitcnt vmcnt(8)
	s_waitcnt lgkmcnt(0)
	s_barrier
	s_setprio 1
	v_mfma_f32_16x16x32_bf16 v[126:129], v[130:133], v[176:179], v[126:129]
	v_mfma_f32_16x16x32_bf16 v[122:125], v[138:141], v[176:179], v[122:125]
	v_mfma_f32_16x16x32_bf16 v[110:113], v[130:133], v[184:187], v[110:113]
	v_mfma_f32_16x16x32_bf16 v[106:109], v[138:141], v[184:187], v[106:109]
	v_mfma_f32_16x16x32_bf16 v[94:97], v[130:133], v[192:195], v[94:97]
	v_mfma_f32_16x16x32_bf16 v[90:93], v[138:141], v[192:195], v[90:93]
	v_mfma_f32_16x16x32_bf16 v[78:81], v[130:133], v[200:203], v[78:81]
	v_mfma_f32_16x16x32_bf16 v[74:77], v[138:141], v[200:203], v[74:77]
	v_mfma_f32_16x16x32_bf16 v[126:129], v[134:137], v[180:183], v[126:129]
	v_mfma_f32_16x16x32_bf16 v[122:125], v[156:159], v[180:183], v[122:125]
	v_mfma_f32_16x16x32_bf16 v[110:113], v[134:137], v[188:191], v[110:113]
	v_mfma_f32_16x16x32_bf16 v[106:109], v[156:159], v[188:191], v[106:109]
	v_mfma_f32_16x16x32_bf16 v[94:97], v[134:137], v[196:199], v[94:97]
	v_mfma_f32_16x16x32_bf16 v[90:93], v[156:159], v[196:199], v[90:93]
	v_mfma_f32_16x16x32_bf16 v[78:81], v[134:137], v[226:229], v[78:81]
	v_mfma_f32_16x16x32_bf16 v[74:77], v[156:159], v[226:229], v[74:77]
	s_setprio 0
	s_setprio 1
	v_mfma_f32_16x16x32_bf16 v[118:121], v[160:163], v[176:179], v[118:121]
	v_mfma_f32_16x16x32_bf16 v[114:117], v[168:171], v[176:179], v[114:117]
	v_mfma_f32_16x16x32_bf16 v[102:105], v[160:163], v[184:187], v[102:105]
	v_mfma_f32_16x16x32_bf16 v[98:101], v[168:171], v[184:187], v[98:101]
	v_mfma_f32_16x16x32_bf16 v[86:89], v[160:163], v[192:195], v[86:89]
	v_mfma_f32_16x16x32_bf16 v[82:85], v[168:171], v[192:195], v[82:85]
	v_mfma_f32_16x16x32_bf16 v[70:73], v[160:163], v[200:203], v[70:73]
	v_mfma_f32_16x16x32_bf16 v[66:69], v[168:171], v[200:203], v[66:69]
	v_mfma_f32_16x16x32_bf16 v[118:121], v[164:167], v[180:183], v[118:121]
	v_mfma_f32_16x16x32_bf16 v[114:117], v[172:175], v[180:183], v[114:117]
	v_mfma_f32_16x16x32_bf16 v[102:105], v[164:167], v[188:191], v[102:105]
	v_mfma_f32_16x16x32_bf16 v[98:101], v[172:175], v[188:191], v[98:101]
	v_mfma_f32_16x16x32_bf16 v[86:89], v[164:167], v[196:199], v[86:89]
	v_mfma_f32_16x16x32_bf16 v[82:85], v[172:175], v[196:199], v[82:85]
	v_mfma_f32_16x16x32_bf16 v[70:73], v[164:167], v[226:229], v[70:73]
	v_mfma_f32_16x16x32_bf16 v[66:69], v[172:175], v[226:229], v[66:69]
	s_setprio 0
	s_barrier
	s_add_i32 s34, s34, s29
	s_mov_b32 m0, s34
	ds_read_b128 v[176:179], v225 offset:16384
	ds_read_b128 v[180:183], v225 offset:17408
	ds_read_b128 v[184:187], v225 offset:18432
	ds_read_b128 v[188:191], v225 offset:19456
	ds_read_b128 v[192:195], v225 offset:20480
	ds_read_b128 v[196:199], v225 offset:21504
	ds_read_b128 v[200:203], v225 offset:22528
	ds_read_b128 v[226:229], v225 offset:23552
	global_load_lds_dwordx4 v0, s[72:73]
	s_add_i32 m0, s34, 0x2000
	s_mov_b64 s[98:99], s[72:73]
	s_add_i32 s33, s33, s29
	global_load_lds_dwordx4 v150, s[72:73]
	s_add_u32 s72, s72, s46
	s_addc_u32 s73, s73, 0
	s_mov_b32 m0, s33
	s_mov_b64 s[100:101], s[10:11]
	global_load_lds_dwordx4 v0, s[72:73]
	s_add_i32 m0, s33, 0x2000
	s_nop 0
	global_load_lds_dwordx4 v150, s[72:73]
	s_mov_b32 m0, s20
	s_nop 0
	global_load_lds_dwordx4 v146, s[10:11]
	s_mov_b32 m0, s35
	s_nop 0
	global_load_lds_dwordx4 v148, s[10:11]
	s_waitcnt vmcnt(8)
	s_waitcnt lgkmcnt(0)
	s_barrier
	s_setprio 1
	v_mfma_f32_16x16x32_bf16 v[62:65], v[130:133], v[176:179], v[62:65]
	v_mfma_f32_16x16x32_bf16 v[58:61], v[138:141], v[176:179], v[58:61]
	v_mfma_f32_16x16x32_bf16 v[46:49], v[130:133], v[184:187], v[46:49]
	v_mfma_f32_16x16x32_bf16 v[42:45], v[138:141], v[184:187], v[42:45]
	v_mfma_f32_16x16x32_bf16 v[30:33], v[130:133], v[192:195], v[30:33]
	v_mfma_f32_16x16x32_bf16 v[26:29], v[138:141], v[192:195], v[26:29]
	v_mfma_f32_16x16x32_bf16 v[14:17], v[130:133], v[200:203], v[14:17]
	v_mfma_f32_16x16x32_bf16 v[10:13], v[138:141], v[200:203], v[10:13]
	v_mfma_f32_16x16x32_bf16 v[62:65], v[134:137], v[180:183], v[62:65]
	v_mfma_f32_16x16x32_bf16 v[58:61], v[156:159], v[180:183], v[58:61]
	v_mfma_f32_16x16x32_bf16 v[46:49], v[134:137], v[188:191], v[46:49]
	v_mfma_f32_16x16x32_bf16 v[42:45], v[156:159], v[188:191], v[42:45]
	v_mfma_f32_16x16x32_bf16 v[30:33], v[134:137], v[196:199], v[30:33]
	v_mfma_f32_16x16x32_bf16 v[26:29], v[156:159], v[196:199], v[26:29]
	v_mfma_f32_16x16x32_bf16 v[14:17], v[134:137], v[226:229], v[14:17]
	v_mfma_f32_16x16x32_bf16 v[10:13], v[156:159], v[226:229], v[10:13]
	s_setprio 0
	s_setprio 1
	v_mfma_f32_16x16x32_bf16 v[54:57], v[160:163], v[176:179], v[54:57]
	v_mfma_f32_16x16x32_bf16 v[50:53], v[168:171], v[176:179], v[50:53]
	v_mfma_f32_16x16x32_bf16 v[38:41], v[160:163], v[184:187], v[38:41]
	v_mfma_f32_16x16x32_bf16 v[34:37], v[168:171], v[184:187], v[34:37]
	v_mfma_f32_16x16x32_bf16 v[22:25], v[160:163], v[192:195], v[22:25]
	v_mfma_f32_16x16x32_bf16 v[18:21], v[168:171], v[192:195], v[18:21]
	v_mfma_f32_16x16x32_bf16 v[6:9], v[160:163], v[200:203], v[6:9]
	v_mfma_f32_16x16x32_bf16 v[2:5], v[168:171], v[200:203], v[2:5]
	v_mfma_f32_16x16x32_bf16 v[54:57], v[164:167], v[180:183], v[54:57]
	v_mfma_f32_16x16x32_bf16 v[50:53], v[172:175], v[180:183], v[50:53]
	v_mfma_f32_16x16x32_bf16 v[38:41], v[164:167], v[188:191], v[38:41]
	v_mfma_f32_16x16x32_bf16 v[34:37], v[172:175], v[188:191], v[34:37]
	v_mfma_f32_16x16x32_bf16 v[22:25], v[164:167], v[196:199], v[22:25]
	v_mfma_f32_16x16x32_bf16 v[18:21], v[172:175], v[196:199], v[18:21]
	v_mfma_f32_16x16x32_bf16 v[6:9], v[164:167], v[226:229], v[6:9]
	v_mfma_f32_16x16x32_bf16 v[2:5], v[172:175], v[226:229], v[2:5]
	s_setprio 0
	s_barrier
	s_add_i32 s33, 0, 0x18000
	s_add_i32 s34, 0, 0x1c000
	ds_read_b128 v[130:133], v232
	ds_read_b128 v[134:137], v232 offset:1024
	ds_read_b128 v[138:141], v232 offset:2048
	ds_read_b128 v[156:159], v232 offset:3072
	ds_read_b128 v[160:163], v233
	ds_read_b128 v[164:167], v233 offset:1024
	ds_read_b128 v[168:171], v233 offset:2048
	ds_read_b128 v[172:175], v233 offset:3072
	s_add_u32 s10, s10, s46
	s_addc_u32 s11, s11, 0
	s_mov_b32 m0, s93
	ds_read_b128 v[176:179], v225 offset:32768
	ds_read_b128 v[180:183], v225 offset:33792
	ds_read_b128 v[184:187], v225 offset:34816
	ds_read_b128 v[188:191], v225 offset:35840
	ds_read_b128 v[192:195], v225 offset:36864
	ds_read_b128 v[196:199], v225 offset:37888
	ds_read_b128 v[200:203], v225 offset:38912
	ds_read_b128 v[226:229], v225 offset:39936
	global_load_lds_dwordx4 v146, s[10:11]
	s_mov_b32 m0, s83
	s_nop 0
	global_load_lds_dwordx4 v148, s[10:11]
	s_waitcnt vmcnt(8)
	s_waitcnt lgkmcnt(0)
	s_barrier
	s_setprio 1
	v_mfma_f32_16x16x32_bf16 v[126:129], v[130:133], v[176:179], v[126:129]
	v_mfma_f32_16x16x32_bf16 v[122:125], v[138:141], v[176:179], v[122:125]
	v_mfma_f32_16x16x32_bf16 v[110:113], v[130:133], v[184:187], v[110:113]
	v_mfma_f32_16x16x32_bf16 v[106:109], v[138:141], v[184:187], v[106:109]
	v_mfma_f32_16x16x32_bf16 v[94:97], v[130:133], v[192:195], v[94:97]
	v_mfma_f32_16x16x32_bf16 v[90:93], v[138:141], v[192:195], v[90:93]
	v_mfma_f32_16x16x32_bf16 v[78:81], v[130:133], v[200:203], v[78:81]
	v_mfma_f32_16x16x32_bf16 v[74:77], v[138:141], v[200:203], v[74:77]
	v_mfma_f32_16x16x32_bf16 v[126:129], v[134:137], v[180:183], v[126:129]
	v_mfma_f32_16x16x32_bf16 v[122:125], v[156:159], v[180:183], v[122:125]
	v_mfma_f32_16x16x32_bf16 v[110:113], v[134:137], v[188:191], v[110:113]
	v_mfma_f32_16x16x32_bf16 v[106:109], v[156:159], v[188:191], v[106:109]
	v_mfma_f32_16x16x32_bf16 v[94:97], v[134:137], v[196:199], v[94:97]
	v_mfma_f32_16x16x32_bf16 v[90:93], v[156:159], v[196:199], v[90:93]
	v_mfma_f32_16x16x32_bf16 v[78:81], v[134:137], v[226:229], v[78:81]
	v_mfma_f32_16x16x32_bf16 v[74:77], v[156:159], v[226:229], v[74:77]
	s_setprio 0
	s_setprio 1
	v_mfma_f32_16x16x32_bf16 v[118:121], v[160:163], v[176:179], v[118:121]
	v_mfma_f32_16x16x32_bf16 v[114:117], v[168:171], v[176:179], v[114:117]
	v_mfma_f32_16x16x32_bf16 v[102:105], v[160:163], v[184:187], v[102:105]
	v_mfma_f32_16x16x32_bf16 v[98:101], v[168:171], v[184:187], v[98:101]
	v_mfma_f32_16x16x32_bf16 v[86:89], v[160:163], v[192:195], v[86:89]
	v_mfma_f32_16x16x32_bf16 v[82:85], v[168:171], v[192:195], v[82:85]
	v_mfma_f32_16x16x32_bf16 v[70:73], v[160:163], v[200:203], v[70:73]
	v_mfma_f32_16x16x32_bf16 v[66:69], v[168:171], v[200:203], v[66:69]
	v_mfma_f32_16x16x32_bf16 v[118:121], v[164:167], v[180:183], v[118:121]
	v_mfma_f32_16x16x32_bf16 v[114:117], v[172:175], v[180:183], v[114:117]
	v_mfma_f32_16x16x32_bf16 v[102:105], v[164:167], v[188:191], v[102:105]
	v_mfma_f32_16x16x32_bf16 v[98:101], v[172:175], v[188:191], v[98:101]
	v_mfma_f32_16x16x32_bf16 v[86:89], v[164:167], v[196:199], v[86:89]
	v_mfma_f32_16x16x32_bf16 v[82:85], v[172:175], v[196:199], v[82:85]
	v_mfma_f32_16x16x32_bf16 v[70:73], v[164:167], v[226:229], v[70:73]
	v_mfma_f32_16x16x32_bf16 v[66:69], v[172:175], v[226:229], v[66:69]
	s_setprio 0
	s_barrier
	s_add_i32 s10, s33, s29
	s_mov_b32 m0, s10
	s_add_u32 s98, s98, 0x80
	s_addc_u32 s99, s99, 0
	ds_read_b128 v[176:179], v225 offset:49152
	ds_read_b128 v[180:183], v225 offset:50176
	ds_read_b128 v[184:187], v225 offset:51200
	ds_read_b128 v[188:191], v225 offset:52224
	ds_read_b128 v[192:195], v225 offset:53248
	ds_read_b128 v[196:199], v225 offset:54272
	ds_read_b128 v[200:203], v225 offset:55296
	ds_read_b128 v[226:229], v225 offset:56320
	global_load_lds_dwordx4 v0, s[98:99]
	s_add_i32 m0, s10, 0x2000
	s_add_i32 s10, s34, s29
	global_load_lds_dwordx4 v150, s[98:99]
	s_mov_b32 m0, s10
	s_add_u32 s72, s72, 0x80
	s_addc_u32 s73, s73, 0
	global_load_lds_dwordx4 v0, s[72:73]
	s_add_i32 m0, s10, 0x2000
	s_add_u32 s100, s100, 0x80
	s_addc_u32 s101, s101, 0
	global_load_lds_dwordx4 v150, s[72:73]
	s_mov_b32 m0, s96
	s_nop 0
	global_load_lds_dwordx4 v146, s[100:101]
	s_mov_b32 m0, s97
	s_nop 0
	global_load_lds_dwordx4 v148, s[100:101]
	s_waitcnt vmcnt(8)
	s_waitcnt lgkmcnt(0)
	s_barrier
	s_setprio 1
	v_mfma_f32_16x16x32_bf16 v[62:65], v[130:133], v[176:179], v[62:65]
	v_mfma_f32_16x16x32_bf16 v[58:61], v[138:141], v[176:179], v[58:61]
	v_mfma_f32_16x16x32_bf16 v[46:49], v[130:133], v[184:187], v[46:49]
	v_mfma_f32_16x16x32_bf16 v[42:45], v[138:141], v[184:187], v[42:45]
	v_mfma_f32_16x16x32_bf16 v[30:33], v[130:133], v[192:195], v[30:33]
	v_mfma_f32_16x16x32_bf16 v[26:29], v[138:141], v[192:195], v[26:29]
	v_mfma_f32_16x16x32_bf16 v[14:17], v[130:133], v[200:203], v[14:17]
	v_mfma_f32_16x16x32_bf16 v[10:13], v[138:141], v[200:203], v[10:13]
	v_mfma_f32_16x16x32_bf16 v[62:65], v[134:137], v[180:183], v[62:65]
	v_mfma_f32_16x16x32_bf16 v[58:61], v[156:159], v[180:183], v[58:61]
	v_mfma_f32_16x16x32_bf16 v[46:49], v[134:137], v[188:191], v[46:49]
	v_mfma_f32_16x16x32_bf16 v[42:45], v[156:159], v[188:191], v[42:45]
	v_mfma_f32_16x16x32_bf16 v[30:33], v[134:137], v[196:199], v[30:33]
	v_mfma_f32_16x16x32_bf16 v[26:29], v[156:159], v[196:199], v[26:29]
	v_mfma_f32_16x16x32_bf16 v[14:17], v[134:137], v[226:229], v[14:17]
	v_mfma_f32_16x16x32_bf16 v[10:13], v[156:159], v[226:229], v[10:13]
	s_setprio 0
	s_setprio 1
	v_mfma_f32_16x16x32_bf16 v[54:57], v[160:163], v[176:179], v[54:57]
	v_mfma_f32_16x16x32_bf16 v[50:53], v[168:171], v[176:179], v[50:53]
	v_mfma_f32_16x16x32_bf16 v[38:41], v[160:163], v[184:187], v[38:41]
	v_mfma_f32_16x16x32_bf16 v[34:37], v[168:171], v[184:187], v[34:37]
	v_mfma_f32_16x16x32_bf16 v[22:25], v[160:163], v[192:195], v[22:25]
	v_mfma_f32_16x16x32_bf16 v[18:21], v[168:171], v[192:195], v[18:21]
	v_mfma_f32_16x16x32_bf16 v[6:9], v[160:163], v[200:203], v[6:9]
	v_mfma_f32_16x16x32_bf16 v[2:5], v[168:171], v[200:203], v[2:5]
	v_mfma_f32_16x16x32_bf16 v[54:57], v[164:167], v[180:183], v[54:57]
	v_mfma_f32_16x16x32_bf16 v[50:53], v[172:175], v[180:183], v[50:53]
	v_mfma_f32_16x16x32_bf16 v[38:41], v[164:167], v[188:191], v[38:41]
	v_mfma_f32_16x16x32_bf16 v[34:37], v[172:175], v[188:191], v[34:37]
	v_mfma_f32_16x16x32_bf16 v[22:25], v[164:167], v[196:199], v[22:25]
	v_mfma_f32_16x16x32_bf16 v[18:21], v[172:175], v[196:199], v[18:21]
	v_mfma_f32_16x16x32_bf16 v[6:9], v[164:167], v[226:229], v[6:9]
	v_mfma_f32_16x16x32_bf16 v[2:5], v[172:175], v[226:229], v[2:5]
	s_setprio 0
	s_barrier
	s_add_u32 s57, s57, 0x100
	s_addc_u32 vcc_lo, vcc_lo, 0
	s_add_u32 s38, s38, 0x100
	s_addc_u32 s39, s39, 0
	s_cmp_ge_u32 s52, s22
	s_mov_b32 s10, s52
	s_cbranch_scc0 .LBB0_692
